# code placement: the eight GEMM mainloop heads pinned to 64-byte boundaries
# speedup vs baseline: 1.0112x; 1.0112x over previous
;     __device__ bool next(int i, Unit& u) const { const bool ok = base.next(i >> 1, u); u.sub = i & 1; return ok; }
; #define PG8_ZERO() do { _Pragma("unroll") for (int a = 0; a < 2; ++a) _Pragma("unroll") for (int b = 0; b < 2; ++b) _Pragma("unroll") for (int m = 0; m < 4; ++m) _Pragma("unroll") for (int n = 0; n < 2; ++n) acc[a][b][m][n] = (f32x4){0.f, 0.f, 0.f, 0.f}; } while (0)
; template <class Epi, class Sched>
; __device__ __forceinline__ void gemm_phase(LAS unsigned char* lds, const Gemm g, const Sched& S, const Epi& E, int wid) {
;     ...
;     Unit cur, nxt; int ui = 0;
;     if (!S.next(0, cur)) return;
;     f32x4 acc[2][2][4][2];
;     PG8_ZERO();
;     ...
;         const bool has_next = S.next(ui + 1, nxt);
;         const char* nA = has_next ? (const char*)(nxt.sub ? g.A1 : g.A0) + (size_t)nxt.pm * tstep : cA; const char* nB = has_next ? (const char*)(nxt.sub ? g.B1 : g.B0) + (size_t)nxt.pn * tstep : cB;
;         for (int t = 0; t < nt; t += 2) {
;             const bool last = (t == nt - 2);
;             const char* a1 = cA + (size_t)(t + 1) * kstep;
;             const char* a2 = last ? nA : cA + (size_t)(t + 2) * kstep; const char* b2 = last ? nB : cB + (size_t)(t + 2) * kstep;
;             const char* a3 = a2 + kstep; const char* b3 = b2 + kstep;
.LBB0_196:
	s_ashr_i32 s21, s20, 31
	s_lshl_b64 s[22:23], s[20:21], 19
	s_add_u32 s22, s13, s22
	s_addc_u32 s23, s38, s23
	s_and_b64 s[24:25], s[16:17], exec
	s_cselect_b32 s21, s23, s31
	s_cselect_b32 s27, s22, s30
	s_ashr_i32 s19, s18, 31
	s_lshl_b64 s[24:25], s[18:19], 19
	s_add_u32 s24, s39, s24
	s_addc_u32 s25, s40, s25
	s_and_b64 s[36:37], s[16:17], exec
	s_cselect_b32 s19, s25, s35
	s_cselect_b32 s54, s24, s34
	s_add_u32 s30, s30, 0x40080
	s_addc_u32 s31, s31, 0
	s_add_u32 s55, s34, 0x100
	v_mov_b32_e32 v0, 0
	s_addc_u32 s56, s35, 0
	s_mov_b32 s57, -2
	v_mov_b32_e32 v1, v0
	v_mov_b32_e32 v2, v0
	v_mov_b32_e32 v3, v0
	v_mov_b32_e32 v4, v0
	v_mov_b32_e32 v5, v0
	v_mov_b32_e32 v6, v0
	v_mov_b32_e32 v7, v0
	v_mov_b32_e32 v16, v0
	v_mov_b32_e32 v17, v0
	v_mov_b32_e32 v18, v0
	v_mov_b32_e32 v19, v0
	v_mov_b32_e32 v20, v0
	v_mov_b32_e32 v21, v0
	v_mov_b32_e32 v22, v0
	v_mov_b32_e32 v23, v0
	v_mov_b32_e32 v32, v0
	v_mov_b32_e32 v33, v0
	v_mov_b32_e32 v34, v0
	v_mov_b32_e32 v35, v0
	v_mov_b32_e32 v36, v0
	v_mov_b32_e32 v37, v0
	v_mov_b32_e32 v38, v0
	v_mov_b32_e32 v39, v0
	v_mov_b32_e32 v48, v0
	v_mov_b32_e32 v49, v0
	v_mov_b32_e32 v50, v0
	v_mov_b32_e32 v51, v0
	v_mov_b32_e32 v52, v0
	v_mov_b32_e32 v53, v0
	v_mov_b32_e32 v54, v0
	v_mov_b32_e32 v55, v0
	v_mov_b32_e32 v8, v0
	v_mov_b32_e32 v9, v0
	v_mov_b32_e32 v10, v0
	v_mov_b32_e32 v11, v0
	v_mov_b32_e32 v12, v0
	v_mov_b32_e32 v13, v0
	v_mov_b32_e32 v14, v0
	v_mov_b32_e32 v15, v0
	v_mov_b32_e32 v24, v0
	v_mov_b32_e32 v25, v0
	v_mov_b32_e32 v26, v0
	v_mov_b32_e32 v27, v0
	v_mov_b32_e32 v28, v0
	v_mov_b32_e32 v29, v0
	v_mov_b32_e32 v30, v0
	v_mov_b32_e32 v31, v0
	v_mov_b32_e32 v40, v0
	v_mov_b32_e32 v41, v0
	v_mov_b32_e32 v42, v0
	v_mov_b32_e32 v43, v0
	v_mov_b32_e32 v44, v0
	v_mov_b32_e32 v45, v0
	v_mov_b32_e32 v46, v0
	v_mov_b32_e32 v47, v0
	v_mov_b32_e32 v56, v0
	v_mov_b32_e32 v57, v0
	v_mov_b32_e32 v58, v0
	v_mov_b32_e32 v59, v0
	v_mov_b32_e32 v60, v0
	v_mov_b32_e32 v61, v0
	v_mov_b32_e32 v62, v0
	v_mov_b32_e32 v63, v0
	v_mov_b32_e32 v64, v0
	v_mov_b32_e32 v65, v0
	v_mov_b32_e32 v66, v0
	v_mov_b32_e32 v67, v0
	v_mov_b32_e32 v68, v0
	v_mov_b32_e32 v69, v0
	v_mov_b32_e32 v70, v0
	v_mov_b32_e32 v71, v0
	v_mov_b32_e32 v80, v0
	v_mov_b32_e32 v81, v0
	v_mov_b32_e32 v82, v0
	v_mov_b32_e32 v83, v0
	v_mov_b32_e32 v84, v0
	v_mov_b32_e32 v85, v0
	v_mov_b32_e32 v86, v0
	v_mov_b32_e32 v87, v0
	v_mov_b32_e32 v96, v0
	v_mov_b32_e32 v97, v0
	v_mov_b32_e32 v98, v0
	v_mov_b32_e32 v99, v0
	v_mov_b32_e32 v100, v0
	v_mov_b32_e32 v101, v0
	v_mov_b32_e32 v102, v0
	v_mov_b32_e32 v103, v0
	v_mov_b32_e32 v112, v0
	v_mov_b32_e32 v113, v0
	v_mov_b32_e32 v114, v0
	v_mov_b32_e32 v115, v0
	v_mov_b32_e32 v116, v0
	v_mov_b32_e32 v117, v0
	v_mov_b32_e32 v118, v0
	v_mov_b32_e32 v119, v0
	v_mov_b32_e32 v72, v0
	v_mov_b32_e32 v73, v0
	v_mov_b32_e32 v74, v0
	v_mov_b32_e32 v75, v0
	v_mov_b32_e32 v76, v0
	v_mov_b32_e32 v77, v0
	v_mov_b32_e32 v78, v0
	v_mov_b32_e32 v79, v0
	v_mov_b32_e32 v88, v0
	v_mov_b32_e32 v89, v0
	v_mov_b32_e32 v90, v0
	v_mov_b32_e32 v91, v0
	v_mov_b32_e32 v92, v0
	v_mov_b32_e32 v93, v0
	v_mov_b32_e32 v94, v0
	v_mov_b32_e32 v95, v0
	v_mov_b32_e32 v104, v0
	v_mov_b32_e32 v105, v0
	v_mov_b32_e32 v106, v0
	v_mov_b32_e32 v107, v0
	v_mov_b32_e32 v108, v0
	v_mov_b32_e32 v109, v0
	v_mov_b32_e32 v110, v0
	v_mov_b32_e32 v111, v0
	v_mov_b32_e32 v120, v0
	v_mov_b32_e32 v121, v0
	v_mov_b32_e32 v122, v0
	v_mov_b32_e32 v123, v0
	v_mov_b32_e32 v124, v0
	v_mov_b32_e32 v125, v0
	v_mov_b32_e32 v126, v0
	v_mov_b32_e32 v127, v0
	.p2alignl 6, 3212836864

;     __device__ bool next(int i, Unit& u) const { const bool ok = base.next(i >> 1, u); u.sub = i & 1; return ok; }
; #define PG8_ZERO() do { _Pragma("unroll") for (int a = 0; a < 2; ++a) _Pragma("unroll") for (int b = 0; b < 2; ++b) _Pragma("unroll") for (int m = 0; m < 4; ++m) _Pragma("unroll") for (int n = 0; n < 2; ++n) acc[a][b][m][n] = (f32x4){0.f, 0.f, 0.f, 0.f}; } while (0)
; template <class Epi, class Sched>
; __device__ __forceinline__ void gemm_phase(LAS unsigned char* lds, const Gemm g, const Sched& S, const Epi& E, int wid) {
;     ...
;     Unit cur, nxt; int ui = 0;
;     if (!S.next(0, cur)) return;
;     f32x4 acc[2][2][4][2];
;     PG8_ZERO();
;     ...
;         const bool has_next = S.next(ui + 1, nxt);
;         const char* nA = has_next ? (const char*)(nxt.sub ? g.A1 : g.A0) + (size_t)nxt.pm * tstep : cA; const char* nB = has_next ? (const char*)(nxt.sub ? g.B1 : g.B0) + (size_t)nxt.pn * tstep : cB;
;         for (int t = 0; t < nt; t += 2) {
;             const bool last = (t == nt - 2);
;             const char* a1 = cA + (size_t)(t + 1) * kstep;
;             const char* a2 = last ? nA : cA + (size_t)(t + 2) * kstep; const char* b2 = last ? nB : cB + (size_t)(t + 2) * kstep;
;             const char* a3 = a2 + kstep; const char* b3 = b2 + kstep;
.LBB0_474:
	s_ashr_i32 s17, s16, 31
	s_lshl_b64 s[18:19], s[16:17], 19
	s_add_u32 s18, s86, s18
	s_addc_u32 s19, s87, s19
	s_and_b64 s[20:21], s[4:5], exec
	s_cselect_b32 s17, s19, s25
	s_cselect_b32 s23, s18, s24
	s_ashr_i32 s15, s14, 31
	s_lshl_b64 s[20:21], s[14:15], 19
	s_add_u32 s20, s30, s20
	s_addc_u32 s21, s31, s21
	s_and_b64 s[28:29], s[4:5], exec
	s_cselect_b32 s15, s21, s27
	s_cselect_b32 s48, s20, s26
	s_add_u32 s24, s24, 0x40080
	s_addc_u32 s25, s25, 0
	s_add_u32 s49, s26, 0x100
	v_mov_b32_e32 v0, 0
	s_addc_u32 s50, s27, 0
	s_mov_b32 s51, -2
	v_mov_b32_e32 v1, v0
	v_mov_b32_e32 v2, v0
	v_mov_b32_e32 v3, v0
	v_mov_b32_e32 v8, v0
	v_mov_b32_e32 v9, v0
	v_mov_b32_e32 v10, v0
	v_mov_b32_e32 v11, v0
	v_mov_b32_e32 v16, v0
	v_mov_b32_e32 v17, v0
	v_mov_b32_e32 v18, v0
	v_mov_b32_e32 v19, v0
	v_mov_b32_e32 v24, v0
	v_mov_b32_e32 v25, v0
	v_mov_b32_e32 v26, v0
	v_mov_b32_e32 v27, v0
	v_mov_b32_e32 v32, v0
	v_mov_b32_e32 v33, v0
	v_mov_b32_e32 v34, v0
	v_mov_b32_e32 v35, v0
	v_mov_b32_e32 v40, v0
	v_mov_b32_e32 v41, v0
	v_mov_b32_e32 v42, v0
	v_mov_b32_e32 v43, v0
	v_mov_b32_e32 v48, v0
	v_mov_b32_e32 v49, v0
	v_mov_b32_e32 v50, v0
	v_mov_b32_e32 v51, v0
	v_mov_b32_e32 v56, v0
	v_mov_b32_e32 v57, v0
	v_mov_b32_e32 v58, v0
	v_mov_b32_e32 v59, v0
	v_mov_b32_e32 v4, v0
	v_mov_b32_e32 v5, v0
	v_mov_b32_e32 v6, v0
	v_mov_b32_e32 v7, v0
	v_mov_b32_e32 v12, v0
	v_mov_b32_e32 v13, v0
	v_mov_b32_e32 v14, v0
	v_mov_b32_e32 v15, v0
	v_mov_b32_e32 v20, v0
	v_mov_b32_e32 v21, v0
	v_mov_b32_e32 v22, v0
	v_mov_b32_e32 v23, v0
	v_mov_b32_e32 v28, v0
	v_mov_b32_e32 v29, v0
	v_mov_b32_e32 v30, v0
	v_mov_b32_e32 v31, v0
	v_mov_b32_e32 v36, v0
	v_mov_b32_e32 v37, v0
	v_mov_b32_e32 v38, v0
	v_mov_b32_e32 v39, v0
	v_mov_b32_e32 v44, v0
	v_mov_b32_e32 v45, v0
	v_mov_b32_e32 v46, v0
	v_mov_b32_e32 v47, v0
	v_mov_b32_e32 v52, v0
	v_mov_b32_e32 v53, v0
	v_mov_b32_e32 v54, v0
	v_mov_b32_e32 v55, v0
	v_mov_b32_e32 v60, v0
	v_mov_b32_e32 v61, v0
	v_mov_b32_e32 v62, v0
	v_mov_b32_e32 v63, v0
	v_mov_b32_e32 v64, v0
	v_mov_b32_e32 v65, v0
	v_mov_b32_e32 v66, v0
	v_mov_b32_e32 v67, v0
	v_mov_b32_e32 v72, v0
	v_mov_b32_e32 v73, v0
	v_mov_b32_e32 v74, v0
	v_mov_b32_e32 v75, v0
	v_mov_b32_e32 v80, v0
	v_mov_b32_e32 v81, v0
	v_mov_b32_e32 v82, v0
	v_mov_b32_e32 v83, v0
	v_mov_b32_e32 v88, v0
	v_mov_b32_e32 v89, v0
	v_mov_b32_e32 v90, v0
	v_mov_b32_e32 v91, v0
	v_mov_b32_e32 v96, v0
	v_mov_b32_e32 v97, v0
	v_mov_b32_e32 v98, v0
	v_mov_b32_e32 v99, v0
	v_mov_b32_e32 v104, v0
	v_mov_b32_e32 v105, v0
	v_mov_b32_e32 v106, v0
	v_mov_b32_e32 v107, v0
	v_mov_b32_e32 v112, v0
	v_mov_b32_e32 v113, v0
	v_mov_b32_e32 v114, v0
	v_mov_b32_e32 v115, v0
	v_mov_b32_e32 v120, v0
	v_mov_b32_e32 v121, v0
	v_mov_b32_e32 v122, v0
	v_mov_b32_e32 v123, v0
	v_mov_b32_e32 v68, v0
	v_mov_b32_e32 v69, v0
	v_mov_b32_e32 v70, v0
	v_mov_b32_e32 v71, v0
	v_mov_b32_e32 v76, v0
	v_mov_b32_e32 v77, v0
	v_mov_b32_e32 v78, v0
	v_mov_b32_e32 v79, v0
	v_mov_b32_e32 v84, v0
	v_mov_b32_e32 v85, v0
	v_mov_b32_e32 v86, v0
	v_mov_b32_e32 v87, v0
	v_mov_b32_e32 v92, v0
	v_mov_b32_e32 v93, v0
	v_mov_b32_e32 v94, v0
	v_mov_b32_e32 v95, v0
	v_mov_b32_e32 v100, v0
	v_mov_b32_e32 v101, v0
	v_mov_b32_e32 v102, v0
	v_mov_b32_e32 v103, v0
	v_mov_b32_e32 v108, v0
	v_mov_b32_e32 v109, v0
	v_mov_b32_e32 v110, v0
	v_mov_b32_e32 v111, v0
	v_mov_b32_e32 v116, v0
	v_mov_b32_e32 v117, v0
	v_mov_b32_e32 v118, v0
	v_mov_b32_e32 v119, v0
	v_mov_b32_e32 v124, v0
	v_mov_b32_e32 v125, v0
	v_mov_b32_e32 v126, v0
	v_mov_b32_e32 v127, v0
	.p2alignl 6, 3212836864

;     __device__ bool next(int i, Unit& u) const { const bool ok = base.next(i >> 1, u); u.sub = i & 1; return ok; }
; #define PG8_ZERO() do { _Pragma("unroll") for (int a = 0; a < 2; ++a) _Pragma("unroll") for (int b = 0; b < 2; ++b) _Pragma("unroll") for (int m = 0; m < 4; ++m) _Pragma("unroll") for (int n = 0; n < 2; ++n) acc[a][b][m][n] = (f32x4){0.f, 0.f, 0.f, 0.f}; } while (0)
; template <class Epi, class Sched>
; __device__ __forceinline__ void gemm_phase(LAS unsigned char* lds, const Gemm g, const Sched& S, const Epi& E, int wid) {
;     ...
;     Unit cur, nxt; int ui = 0;
;     if (!S.next(0, cur)) return;
;     f32x4 acc[2][2][4][2];
;     PG8_ZERO();
;     ...
;         for (int t = 0; t < nt; t += 2) {
;             const bool last = (t == nt - 2);
;             const char* a1 = cA + (size_t)(t + 1) * kstep;
;             const char* a2 = last ? nA : cA + (size_t)(t + 2) * kstep; const char* b2 = last ? nB : cB + (size_t)(t + 2) * kstep;
;             const char* a3 = a2 + kstep; const char* b3 = b2 + kstep;
.LBB0_572:
	s_add_u32 s35, s4, 0x100
	v_mov_b32_e32 v0, 0
	s_addc_u32 s37, s5, 0
	s_mov_b32 s40, -2
	v_mov_b32_e32 v1, v0
	v_mov_b32_e32 v2, v0
	v_mov_b32_e32 v3, v0
	v_mov_b32_e32 v4, v0
	v_mov_b32_e32 v5, v0
	v_mov_b32_e32 v6, v0
	v_mov_b32_e32 v7, v0
	v_mov_b32_e32 v16, v0
	v_mov_b32_e32 v17, v0
	v_mov_b32_e32 v18, v0
	v_mov_b32_e32 v19, v0
	v_mov_b32_e32 v24, v0
	v_mov_b32_e32 v25, v0
	v_mov_b32_e32 v26, v0
	v_mov_b32_e32 v27, v0
	v_mov_b32_e32 v44, v0
	v_mov_b32_e32 v45, v0
	v_mov_b32_e32 v46, v0
	v_mov_b32_e32 v47, v0
	v_mov_b32_e32 v52, v0
	v_mov_b32_e32 v53, v0
	v_mov_b32_e32 v54, v0
	v_mov_b32_e32 v55, v0
	v_mov_b32_e32 v76, v0
	v_mov_b32_e32 v77, v0
	v_mov_b32_e32 v78, v0
	v_mov_b32_e32 v79, v0
	v_mov_b32_e32 v92, v0
	v_mov_b32_e32 v93, v0
	v_mov_b32_e32 v94, v0
	v_mov_b32_e32 v95, v0
	v_mov_b32_e32 v8, v0
	v_mov_b32_e32 v9, v0
	v_mov_b32_e32 v10, v0
	v_mov_b32_e32 v11, v0
	v_mov_b32_e32 v12, v0
	v_mov_b32_e32 v13, v0
	v_mov_b32_e32 v14, v0
	v_mov_b32_e32 v15, v0
	v_mov_b32_e32 v32, v0
	v_mov_b32_e32 v33, v0
	v_mov_b32_e32 v34, v0
	v_mov_b32_e32 v35, v0
	v_mov_b32_e32 v36, v0
	v_mov_b32_e32 v37, v0
	v_mov_b32_e32 v38, v0
	v_mov_b32_e32 v39, v0
	v_mov_b32_e32 v68, v0
	v_mov_b32_e32 v69, v0
	v_mov_b32_e32 v70, v0
	v_mov_b32_e32 v71, v0
	v_mov_b32_e32 v72, v0
	v_mov_b32_e32 v73, v0
	v_mov_b32_e32 v74, v0
	v_mov_b32_e32 v75, v0
	v_mov_b32_e32 v100, v0
	v_mov_b32_e32 v101, v0
	v_mov_b32_e32 v102, v0
	v_mov_b32_e32 v103, v0
	v_mov_b32_e32 v108, v0
	v_mov_b32_e32 v109, v0
	v_mov_b32_e32 v110, v0
	v_mov_b32_e32 v111, v0
	v_mov_b32_e32 v104, v0
	v_mov_b32_e32 v105, v0
	v_mov_b32_e32 v106, v0
	v_mov_b32_e32 v107, v0
	v_mov_b32_e32 v96, v0
	v_mov_b32_e32 v97, v0
	v_mov_b32_e32 v98, v0
	v_mov_b32_e32 v99, v0
	v_mov_b32_e32 v80, v0
	v_mov_b32_e32 v81, v0
	v_mov_b32_e32 v82, v0
	v_mov_b32_e32 v83, v0
	v_mov_b32_e32 v64, v0
	v_mov_b32_e32 v65, v0
	v_mov_b32_e32 v66, v0
	v_mov_b32_e32 v67, v0
	v_mov_b32_e32 v48, v0
	v_mov_b32_e32 v49, v0
	v_mov_b32_e32 v50, v0
	v_mov_b32_e32 v51, v0
	v_mov_b32_e32 v40, v0
	v_mov_b32_e32 v41, v0
	v_mov_b32_e32 v42, v0
	v_mov_b32_e32 v43, v0
	v_mov_b32_e32 v28, v0
	v_mov_b32_e32 v29, v0
	v_mov_b32_e32 v30, v0
	v_mov_b32_e32 v31, v0
	v_mov_b32_e32 v20, v0
	v_mov_b32_e32 v21, v0
	v_mov_b32_e32 v22, v0
	v_mov_b32_e32 v23, v0
	v_mov_b32_e32 v124, v0
	v_mov_b32_e32 v125, v0
	v_mov_b32_e32 v126, v0
	v_mov_b32_e32 v127, v0
	v_mov_b32_e32 v120, v0
	v_mov_b32_e32 v121, v0
	v_mov_b32_e32 v122, v0
	v_mov_b32_e32 v123, v0
	v_mov_b32_e32 v116, v0
	v_mov_b32_e32 v117, v0
	v_mov_b32_e32 v118, v0
	v_mov_b32_e32 v119, v0
	v_mov_b32_e32 v112, v0
	v_mov_b32_e32 v113, v0
	v_mov_b32_e32 v114, v0
	v_mov_b32_e32 v115, v0
	v_mov_b32_e32 v88, v0
	v_mov_b32_e32 v89, v0
	v_mov_b32_e32 v90, v0
	v_mov_b32_e32 v91, v0
	v_mov_b32_e32 v84, v0
	v_mov_b32_e32 v85, v0
	v_mov_b32_e32 v86, v0
	v_mov_b32_e32 v87, v0
	v_mov_b32_e32 v60, v0
	v_mov_b32_e32 v61, v0
	v_mov_b32_e32 v62, v0
	v_mov_b32_e32 v63, v0
	v_mov_b32_e32 v56, v0
	v_mov_b32_e32 v57, v0
	v_mov_b32_e32 v58, v0
	v_mov_b32_e32 v59, v0
	.p2alignl 6, 3212836864

;     __device__ bool next(int i, Unit& u) const { const bool ok = base.next(i >> 1, u); u.sub = i & 1; return ok; }
; #define PG8_ZERO() do { _Pragma("unroll") for (int a = 0; a < 2; ++a) _Pragma("unroll") for (int b = 0; b < 2; ++b) _Pragma("unroll") for (int m = 0; m < 4; ++m) _Pragma("unroll") for (int n = 0; n < 2; ++n) acc[a][b][m][n] = (f32x4){0.f, 0.f, 0.f, 0.f}; } while (0)
; template <class Epi, class Sched>
; __device__ __forceinline__ void gemm_phase(LAS unsigned char* lds, const Gemm g, const Sched& S, const Epi& E, int wid) {
;     ...
;     Unit cur, nxt; int ui = 0;
;     if (!S.next(0, cur)) return;
;     f32x4 acc[2][2][4][2];
;     PG8_ZERO();
;     ...
;         const bool has_next = S.next(ui + 1, nxt);
;         const char* nA = has_next ? (const char*)(nxt.sub ? g.A1 : g.A0) + (size_t)nxt.pm * tstep : cA; const char* nB = has_next ? (const char*)(nxt.sub ? g.B1 : g.B0) + (size_t)nxt.pn * tstep : cB;
;         for (int t = 0; t < nt; t += 2) {
;             const bool last = (t == nt - 2);
;             const char* a1 = cA + (size_t)(t + 1) * kstep;
;             const char* a2 = last ? nA : cA + (size_t)(t + 2) * kstep; const char* b2 = last ? nB : cB + (size_t)(t + 2) * kstep;
;             const char* a3 = a2 + kstep; const char* b3 = b2 + kstep;
.LBB0_742:
	s_ashr_i32 s37, s36, 31
	s_lshl_b64 s[14:15], s[36:37], 19
	s_add_u32 s38, s86, s14
	s_addc_u32 s39, s87, s15
	s_and_b64 s[14:15], s[10:11], exec
	s_cselect_b32 s13, s39, s7
	s_cselect_b32 s37, s38, s6
	s_ashr_i32 s35, s34, 31
	s_lshl_b64 s[14:15], s[34:35], 19
	s_add_u32 s40, s54, s14
	s_addc_u32 s41, s55, s15
	s_and_b64 s[14:15], s[10:11], exec
	s_cselect_b32 s35, s41, s5
	s_cselect_b32 s42, s40, s4
	s_add_u32 s6, s6, 0x40080
	s_addc_u32 s7, s7, 0
	s_add_u32 s43, s4, 0x100
	v_mov_b32_e32 v64, 0
	s_addc_u32 s44, s5, 0
	s_mov_b32 s45, -2
	v_mov_b32_e32 v65, v64
	v_mov_b32_e32 v66, v64
	v_mov_b32_e32 v67, v64
	v_mov_b32_e32 v68, v64
	v_mov_b32_e32 v69, v64
	v_mov_b32_e32 v70, v64
	v_mov_b32_e32 v71, v64
	v_mov_b32_e32 v72, v64
	v_mov_b32_e32 v73, v64
	v_mov_b32_e32 v74, v64
	v_mov_b32_e32 v75, v64
	v_mov_b32_e32 v76, v64
	v_mov_b32_e32 v77, v64
	v_mov_b32_e32 v78, v64
	v_mov_b32_e32 v79, v64
	v_mov_b32_e32 v80, v64
	v_mov_b32_e32 v81, v64
	v_mov_b32_e32 v82, v64
	v_mov_b32_e32 v83, v64
	v_mov_b32_e32 v84, v64
	v_mov_b32_e32 v85, v64
	v_mov_b32_e32 v86, v64
	v_mov_b32_e32 v87, v64
	v_mov_b32_e32 v88, v64
	v_mov_b32_e32 v89, v64
	v_mov_b32_e32 v90, v64
	v_mov_b32_e32 v91, v64
	v_mov_b32_e32 v92, v64
	v_mov_b32_e32 v93, v64
	v_mov_b32_e32 v94, v64
	v_mov_b32_e32 v95, v64
	v_mov_b32_e32 v0, v64
	v_mov_b32_e32 v1, v64
	v_mov_b32_e32 v2, v64
	v_mov_b32_e32 v3, v64
	v_mov_b32_e32 v4, v64
	v_mov_b32_e32 v5, v64
	v_mov_b32_e32 v6, v64
	v_mov_b32_e32 v7, v64
	v_mov_b32_e32 v8, v64
	v_mov_b32_e32 v9, v64
	v_mov_b32_e32 v10, v64
	v_mov_b32_e32 v11, v64
	v_mov_b32_e32 v12, v64
	v_mov_b32_e32 v13, v64
	v_mov_b32_e32 v14, v64
	v_mov_b32_e32 v15, v64
	v_mov_b32_e32 v16, v64
	v_mov_b32_e32 v17, v64
	v_mov_b32_e32 v18, v64
	v_mov_b32_e32 v19, v64
	v_mov_b32_e32 v20, v64
	v_mov_b32_e32 v21, v64
	v_mov_b32_e32 v22, v64
	v_mov_b32_e32 v23, v64
	v_mov_b32_e32 v24, v64
	v_mov_b32_e32 v25, v64
	v_mov_b32_e32 v26, v64
	v_mov_b32_e32 v27, v64
	v_mov_b32_e32 v28, v64
	v_mov_b32_e32 v29, v64
	v_mov_b32_e32 v30, v64
	v_mov_b32_e32 v31, v64
	v_mov_b32_e32 v96, v64
	v_mov_b32_e32 v97, v64
	v_mov_b32_e32 v98, v64
	v_mov_b32_e32 v99, v64
	v_mov_b32_e32 v100, v64
	v_mov_b32_e32 v101, v64
	v_mov_b32_e32 v102, v64
	v_mov_b32_e32 v103, v64
	v_mov_b32_e32 v104, v64
	v_mov_b32_e32 v105, v64
	v_mov_b32_e32 v106, v64
	v_mov_b32_e32 v107, v64
	v_mov_b32_e32 v108, v64
	v_mov_b32_e32 v109, v64
	v_mov_b32_e32 v110, v64
	v_mov_b32_e32 v111, v64
	v_mov_b32_e32 v112, v64
	v_mov_b32_e32 v113, v64
	v_mov_b32_e32 v114, v64
	v_mov_b32_e32 v115, v64
	v_mov_b32_e32 v116, v64
	v_mov_b32_e32 v117, v64
	v_mov_b32_e32 v118, v64
	v_mov_b32_e32 v119, v64
	v_mov_b32_e32 v120, v64
	v_mov_b32_e32 v121, v64
	v_mov_b32_e32 v122, v64
	v_mov_b32_e32 v123, v64
	v_mov_b32_e32 v124, v64
	v_mov_b32_e32 v125, v64
	v_mov_b32_e32 v126, v64
	v_mov_b32_e32 v127, v64
	v_mov_b32_e32 v32, v64
	v_mov_b32_e32 v33, v64
	v_mov_b32_e32 v34, v64
	v_mov_b32_e32 v35, v64
	v_mov_b32_e32 v36, v64
	v_mov_b32_e32 v37, v64
	v_mov_b32_e32 v38, v64
	v_mov_b32_e32 v39, v64
	v_mov_b32_e32 v40, v64
	v_mov_b32_e32 v41, v64
	v_mov_b32_e32 v42, v64
	v_mov_b32_e32 v43, v64
	v_mov_b32_e32 v44, v64
	v_mov_b32_e32 v45, v64
	v_mov_b32_e32 v46, v64
	v_mov_b32_e32 v47, v64
	v_mov_b32_e32 v48, v64
	v_mov_b32_e32 v49, v64
	v_mov_b32_e32 v50, v64
	v_mov_b32_e32 v51, v64
	v_mov_b32_e32 v52, v64
	v_mov_b32_e32 v53, v64
	v_mov_b32_e32 v54, v64
	v_mov_b32_e32 v55, v64
	v_mov_b32_e32 v56, v64
	v_mov_b32_e32 v57, v64
	v_mov_b32_e32 v58, v64
	v_mov_b32_e32 v59, v64
	v_mov_b32_e32 v60, v64
	v_mov_b32_e32 v61, v64
	v_mov_b32_e32 v62, v64
	v_mov_b32_e32 v63, v64
	.p2alignl 6, 3212836864

;     __device__ bool next(int i, Unit& u) const { const bool ok = base.next(i >> 1, u); u.sub = i & 1; return ok; }
; template <class Epi, class Sched>
; __device__ __forceinline__ void gemm_phase(LAS unsigned char* lds, const Gemm g, const Sched& S, const Epi& E, int wid) {
;     ...
;         const bool has_next = S.next(ui + 1, nxt);
;         const char* nA = has_next ? (const char*)(nxt.sub ? g.A1 : g.A0) + (size_t)nxt.pm * tstep : cA; const char* nB = has_next ? (const char*)(nxt.sub ? g.B1 : g.B0) + (size_t)nxt.pn * tstep : cB;
;         for (int t = 0; t < nt; t += 2) {
;             const bool last = (t == nt - 2);
;             const char* a1 = cA + (size_t)(t + 1) * kstep;
;             const char* a2 = last ? nA : cA + (size_t)(t + 2) * kstep; const char* b2 = last ? nB : cB + (size_t)(t + 2) * kstep;
;             const char* a3 = a2 + kstep; const char* b3 = b2 + kstep;
.LBB0_1908:
	s_ashr_i32 s29, s28, 31
	s_and_b32 s52, s51, 1
	s_lshl_b64 s[30:31], s[28:29], 19
	s_cmp_eq_u32 s52, 0
	s_cselect_b32 s29, s14, s16
	s_cselect_b32 s27, s15, s17
	s_cselect_b32 s40, s12, s18
	s_cselect_b32 s41, s13, s19
	s_add_u32 s30, s29, s30
	s_addc_u32 s31, s27, s31
	s_and_b64 s[34:35], s[8:9], exec
	s_cselect_b32 s29, s31, s5
	s_cselect_b32 s39, s30, s4
	s_ashr_i32 s27, s26, 31
	s_lshl_b64 s[34:35], s[26:27], 19
	s_add_u32 s34, s40, s34
	s_addc_u32 s35, s41, s35
	s_and_b64 s[40:41], s[8:9], exec
	s_cselect_b32 s27, s35, s37
	s_cselect_b32 s53, s34, s36
	s_add_u32 s4, s4, 0x40080
	s_addc_u32 s5, s5, 0
	s_add_u32 s54, s36, 0x100
	s_addc_u32 s55, s37, 0
	s_mov_b32 s56, -2
	.p2alignl 6, 3212836864

;     __device__ bool next(int i, Unit& u) const { const bool ok = base.next(i >> 1, u); u.sub = i & 1; return ok; }
; #define PG8_ZERO() do { _Pragma("unroll") for (int a = 0; a < 2; ++a) _Pragma("unroll") for (int b = 0; b < 2; ++b) _Pragma("unroll") for (int m = 0; m < 4; ++m) _Pragma("unroll") for (int n = 0; n < 2; ++n) acc[a][b][m][n] = (f32x4){0.f, 0.f, 0.f, 0.f}; } while (0)
; template <class Epi, class Sched>
; __device__ __forceinline__ void gemm_phase(LAS unsigned char* lds, const Gemm g, const Sched& S, const Epi& E, int wid) {
;     ...
;     Unit cur, nxt; int ui = 0;
;     if (!S.next(0, cur)) return;
;     f32x4 acc[2][2][4][2];
;     PG8_ZERO();
;     ...
;         const bool has_next = S.next(ui + 1, nxt);
;         const char* nA = has_next ? (const char*)(nxt.sub ? g.A1 : g.A0) + (size_t)nxt.pm * tstep : cA; const char* nB = has_next ? (const char*)(nxt.sub ? g.B1 : g.B0) + (size_t)nxt.pn * tstep : cB;
;         for (int t = 0; t < nt; t += 2) {
;             const bool last = (t == nt - 2);
;             const char* a1 = cA + (size_t)(t + 1) * kstep;
;             const char* a2 = last ? nA : cA + (size_t)(t + 2) * kstep; const char* b2 = last ? nB : cB + (size_t)(t + 2) * kstep;
;             const char* a3 = a2 + kstep; const char* b3 = b2 + kstep;
.LBB0_2013:
	s_ashr_i32 s31, s30, 31
	s_lshl_b64 s[10:11], s[30:31], 19
	s_add_u32 s34, s84, s10
	s_addc_u32 s35, s85, s11
	s_and_b64 s[10:11], s[8:9], exec
	s_cselect_b32 s31, s35, s7
	s_cselect_b32 s39, s34, s6
	s_ashr_i32 s29, s28, 31
	s_lshl_b64 s[10:11], s[28:29], 19
	s_add_u32 s36, s18, s10
	s_addc_u32 s37, s19, s11
	s_and_b64 s[10:11], s[8:9], exec
	s_cselect_b32 s29, s37, s5
	s_cselect_b32 s41, s36, s4
	s_add_u32 s6, s6, 0x40080
	s_addc_u32 s7, s7, 0
	s_add_u32 s42, s4, 0x100
	v_mov_b32_e32 v0, 0
	s_addc_u32 s43, s5, 0
	s_mov_b32 s44, -2
	v_mov_b32_e32 v1, v0
	v_mov_b32_e32 v2, v0
	v_mov_b32_e32 v3, v0
	v_mov_b32_e32 v4, v0
	v_mov_b32_e32 v5, v0
	v_mov_b32_e32 v6, v0
	v_mov_b32_e32 v7, v0
	v_mov_b32_e32 v16, v0
	v_mov_b32_e32 v17, v0
	v_mov_b32_e32 v18, v0
	v_mov_b32_e32 v19, v0
	v_mov_b32_e32 v24, v0
	v_mov_b32_e32 v25, v0
	v_mov_b32_e32 v26, v0
	v_mov_b32_e32 v27, v0
	v_mov_b32_e32 v44, v0
	v_mov_b32_e32 v45, v0
	v_mov_b32_e32 v46, v0
	v_mov_b32_e32 v47, v0
	v_mov_b32_e32 v52, v0
	v_mov_b32_e32 v53, v0
	v_mov_b32_e32 v54, v0
	v_mov_b32_e32 v55, v0
	v_mov_b32_e32 v76, v0
	v_mov_b32_e32 v77, v0
	v_mov_b32_e32 v78, v0
	v_mov_b32_e32 v79, v0
	v_mov_b32_e32 v88, v0
	v_mov_b32_e32 v89, v0
	v_mov_b32_e32 v90, v0
	v_mov_b32_e32 v91, v0
	v_mov_b32_e32 v8, v0
	v_mov_b32_e32 v9, v0
	v_mov_b32_e32 v10, v0
	v_mov_b32_e32 v11, v0
	v_mov_b32_e32 v12, v0
	v_mov_b32_e32 v13, v0
	v_mov_b32_e32 v14, v0
	v_mov_b32_e32 v15, v0
	v_mov_b32_e32 v32, v0
	v_mov_b32_e32 v33, v0
	v_mov_b32_e32 v34, v0
	v_mov_b32_e32 v35, v0
	v_mov_b32_e32 v40, v0
	v_mov_b32_e32 v41, v0
	v_mov_b32_e32 v42, v0
	v_mov_b32_e32 v43, v0
	v_mov_b32_e32 v68, v0
	v_mov_b32_e32 v69, v0
	v_mov_b32_e32 v70, v0
	v_mov_b32_e32 v71, v0
	v_mov_b32_e32 v72, v0
	v_mov_b32_e32 v73, v0
	v_mov_b32_e32 v74, v0
	v_mov_b32_e32 v75, v0
	v_mov_b32_e32 v100, v0
	v_mov_b32_e32 v101, v0
	v_mov_b32_e32 v102, v0
	v_mov_b32_e32 v103, v0
	v_mov_b32_e32 v108, v0
	v_mov_b32_e32 v109, v0
	v_mov_b32_e32 v110, v0
	v_mov_b32_e32 v111, v0
	v_mov_b32_e32 v104, v0
	v_mov_b32_e32 v105, v0
	v_mov_b32_e32 v106, v0
	v_mov_b32_e32 v107, v0
	v_mov_b32_e32 v96, v0
	v_mov_b32_e32 v97, v0
	v_mov_b32_e32 v98, v0
	v_mov_b32_e32 v99, v0
	v_mov_b32_e32 v80, v0
	v_mov_b32_e32 v81, v0
	v_mov_b32_e32 v82, v0
	v_mov_b32_e32 v83, v0
	v_mov_b32_e32 v60, v0
	v_mov_b32_e32 v61, v0
	v_mov_b32_e32 v62, v0
	v_mov_b32_e32 v63, v0
	v_mov_b32_e32 v48, v0
	v_mov_b32_e32 v49, v0
	v_mov_b32_e32 v50, v0
	v_mov_b32_e32 v51, v0
	v_mov_b32_e32 v36, v0
	v_mov_b32_e32 v37, v0
	v_mov_b32_e32 v38, v0
	v_mov_b32_e32 v39, v0
	v_mov_b32_e32 v28, v0
	v_mov_b32_e32 v29, v0
	v_mov_b32_e32 v30, v0
	v_mov_b32_e32 v31, v0
	v_mov_b32_e32 v20, v0
	v_mov_b32_e32 v21, v0
	v_mov_b32_e32 v22, v0
	v_mov_b32_e32 v23, v0
	v_mov_b32_e32 v124, v0
	v_mov_b32_e32 v125, v0
	v_mov_b32_e32 v126, v0
	v_mov_b32_e32 v127, v0
	v_mov_b32_e32 v120, v0
	v_mov_b32_e32 v121, v0
	v_mov_b32_e32 v122, v0
	v_mov_b32_e32 v123, v0
	v_mov_b32_e32 v116, v0
	v_mov_b32_e32 v117, v0
	v_mov_b32_e32 v118, v0
	v_mov_b32_e32 v119, v0
	v_mov_b32_e32 v112, v0
	v_mov_b32_e32 v113, v0
	v_mov_b32_e32 v114, v0
	v_mov_b32_e32 v115, v0
	v_mov_b32_e32 v92, v0
	v_mov_b32_e32 v93, v0
	v_mov_b32_e32 v94, v0
	v_mov_b32_e32 v95, v0
	v_mov_b32_e32 v84, v0
	v_mov_b32_e32 v85, v0
	v_mov_b32_e32 v86, v0
	v_mov_b32_e32 v87, v0
	v_mov_b32_e32 v64, v0
	v_mov_b32_e32 v65, v0
	v_mov_b32_e32 v66, v0
	v_mov_b32_e32 v67, v0
	v_mov_b32_e32 v56, v0
	v_mov_b32_e32 v57, v0
	v_mov_b32_e32 v58, v0
	v_mov_b32_e32 v59, v0
	.p2alignl 6, 3212836864

;     __device__ bool next(int i, Unit& u) const { const bool ok = base.next(i >> 1, u); u.sub = i & 1; return ok; }
; #define PG8_ZERO() do { _Pragma("unroll") for (int a = 0; a < 2; ++a) _Pragma("unroll") for (int b = 0; b < 2; ++b) _Pragma("unroll") for (int m = 0; m < 4; ++m) _Pragma("unroll") for (int n = 0; n < 2; ++n) acc[a][b][m][n] = (f32x4){0.f, 0.f, 0.f, 0.f}; } while (0)
; template <class Epi, class Sched>
; __device__ __forceinline__ void gemm_phase(LAS unsigned char* lds, const Gemm g, const Sched& S, const Epi& E, int wid) {
;     ...
;     Unit cur, nxt; int ui = 0;
;     if (!S.next(0, cur)) return;
;     f32x4 acc[2][2][4][2];
;     PG8_ZERO();
;     ...
;         const bool has_next = S.next(ui + 1, nxt);
;         const char* nA = has_next ? (const char*)(nxt.sub ? g.A1 : g.A0) + (size_t)nxt.pm * tstep : cA; const char* nB = has_next ? (const char*)(nxt.sub ? g.B1 : g.B0) + (size_t)nxt.pn * tstep : cB;
;         for (int t = 0; t < nt; t += 2) {
;             const bool last = (t == nt - 2);
;             const char* a1 = cA + (size_t)(t + 1) * kstep;
;             const char* a2 = last ? nA : cA + (size_t)(t + 2) * kstep; const char* b2 = last ? nB : cB + (size_t)(t + 2) * kstep;
;             const char* a3 = a2 + kstep; const char* b3 = b2 + kstep;
.LBB0_2202:
	s_ashr_i32 s21, s20, 31
	s_lshl_b64 s[22:23], s[20:21], 19
	s_add_u32 s22, s86, s22
	s_addc_u32 s23, s87, s23
	s_and_b64 s[24:25], s[6:7], exec
	s_cselect_b32 s21, s23, s29
	s_cselect_b32 s27, s22, s28
	s_ashr_i32 s19, s18, 31
	s_lshl_b64 s[24:25], s[18:19], 19
	s_add_u32 s24, s3, s24
	s_addc_u32 s25, s34, s25
	s_and_b64 s[30:31], s[6:7], exec
	s_cselect_b32 s19, s25, s5
	s_cselect_b32 s49, s24, s4
	s_add_u32 s28, s28, 0x40080
	s_addc_u32 s29, s29, 0
	s_add_u32 s50, s4, 0x100
	v_mov_b32_e32 v0, 0
	s_addc_u32 s51, s5, 0
	s_mov_b32 s52, -2
	v_mov_b32_e32 v1, v0
	v_mov_b32_e32 v2, v0
	v_mov_b32_e32 v3, v0
	v_mov_b32_e32 v8, v0
	v_mov_b32_e32 v9, v0
	v_mov_b32_e32 v10, v0
	v_mov_b32_e32 v11, v0
	v_mov_b32_e32 v16, v0
	v_mov_b32_e32 v17, v0
	v_mov_b32_e32 v18, v0
	v_mov_b32_e32 v19, v0
	v_mov_b32_e32 v24, v0
	v_mov_b32_e32 v25, v0
	v_mov_b32_e32 v26, v0
	v_mov_b32_e32 v27, v0
	v_mov_b32_e32 v32, v0
	v_mov_b32_e32 v33, v0
	v_mov_b32_e32 v34, v0
	v_mov_b32_e32 v35, v0
	v_mov_b32_e32 v40, v0
	v_mov_b32_e32 v41, v0
	v_mov_b32_e32 v42, v0
	v_mov_b32_e32 v43, v0
	v_mov_b32_e32 v48, v0
	v_mov_b32_e32 v49, v0
	v_mov_b32_e32 v50, v0
	v_mov_b32_e32 v51, v0
	v_mov_b32_e32 v56, v0
	v_mov_b32_e32 v57, v0
	v_mov_b32_e32 v58, v0
	v_mov_b32_e32 v59, v0
	v_mov_b32_e32 v4, v0
	v_mov_b32_e32 v5, v0
	v_mov_b32_e32 v6, v0
	v_mov_b32_e32 v7, v0
	v_mov_b32_e32 v12, v0
	v_mov_b32_e32 v13, v0
	v_mov_b32_e32 v14, v0
	v_mov_b32_e32 v15, v0
	v_mov_b32_e32 v20, v0
	v_mov_b32_e32 v21, v0
	v_mov_b32_e32 v22, v0
	v_mov_b32_e32 v23, v0
	v_mov_b32_e32 v28, v0
	v_mov_b32_e32 v29, v0
	v_mov_b32_e32 v30, v0
	v_mov_b32_e32 v31, v0
	v_mov_b32_e32 v36, v0
	v_mov_b32_e32 v37, v0
	v_mov_b32_e32 v38, v0
	v_mov_b32_e32 v39, v0
	v_mov_b32_e32 v44, v0
	v_mov_b32_e32 v45, v0
	v_mov_b32_e32 v46, v0
	v_mov_b32_e32 v47, v0
	v_mov_b32_e32 v52, v0
	v_mov_b32_e32 v53, v0
	v_mov_b32_e32 v54, v0
	v_mov_b32_e32 v55, v0
	v_mov_b32_e32 v60, v0
	v_mov_b32_e32 v61, v0
	v_mov_b32_e32 v62, v0
	v_mov_b32_e32 v63, v0
	v_mov_b32_e32 v64, v0
	v_mov_b32_e32 v65, v0
	v_mov_b32_e32 v66, v0
	v_mov_b32_e32 v67, v0
	v_mov_b32_e32 v72, v0
	v_mov_b32_e32 v73, v0
	v_mov_b32_e32 v74, v0
	v_mov_b32_e32 v75, v0
	v_mov_b32_e32 v80, v0
	v_mov_b32_e32 v81, v0
	v_mov_b32_e32 v82, v0
	v_mov_b32_e32 v83, v0
	v_mov_b32_e32 v88, v0
	v_mov_b32_e32 v89, v0
	v_mov_b32_e32 v90, v0
	v_mov_b32_e32 v91, v0
	v_mov_b32_e32 v96, v0
	v_mov_b32_e32 v97, v0
	v_mov_b32_e32 v98, v0
	v_mov_b32_e32 v99, v0
	v_mov_b32_e32 v104, v0
	v_mov_b32_e32 v105, v0
	v_mov_b32_e32 v106, v0
	v_mov_b32_e32 v107, v0
	v_mov_b32_e32 v112, v0
	v_mov_b32_e32 v113, v0
	v_mov_b32_e32 v114, v0
	v_mov_b32_e32 v115, v0
	v_mov_b32_e32 v120, v0
	v_mov_b32_e32 v121, v0
	v_mov_b32_e32 v122, v0
	v_mov_b32_e32 v123, v0
	v_mov_b32_e32 v68, v0
	v_mov_b32_e32 v69, v0
	v_mov_b32_e32 v70, v0
	v_mov_b32_e32 v71, v0
	v_mov_b32_e32 v76, v0
	v_mov_b32_e32 v77, v0
	v_mov_b32_e32 v78, v0
	v_mov_b32_e32 v79, v0
	v_mov_b32_e32 v84, v0
	v_mov_b32_e32 v85, v0
	v_mov_b32_e32 v86, v0
	v_mov_b32_e32 v87, v0
	v_mov_b32_e32 v92, v0
	v_mov_b32_e32 v93, v0
	v_mov_b32_e32 v94, v0
	v_mov_b32_e32 v95, v0
	v_mov_b32_e32 v100, v0
	v_mov_b32_e32 v101, v0
	v_mov_b32_e32 v102, v0
	v_mov_b32_e32 v103, v0
	v_mov_b32_e32 v108, v0
	v_mov_b32_e32 v109, v0
	v_mov_b32_e32 v110, v0
	v_mov_b32_e32 v111, v0
	v_mov_b32_e32 v116, v0
	v_mov_b32_e32 v117, v0
	v_mov_b32_e32 v118, v0
	v_mov_b32_e32 v119, v0
	v_mov_b32_e32 v124, v0
	v_mov_b32_e32 v125, v0
	v_mov_b32_e32 v126, v0
	v_mov_b32_e32 v127, v0
	.p2alignl 6, 3212836864

;     __device__ bool next(int i, Unit& u) const { const bool ok = base.next(i >> 1, u); u.sub = i & 1; return ok; }
; #define PG8_ZERO() do { _Pragma("unroll") for (int a = 0; a < 2; ++a) _Pragma("unroll") for (int b = 0; b < 2; ++b) _Pragma("unroll") for (int m = 0; m < 4; ++m) _Pragma("unroll") for (int n = 0; n < 2; ++n) acc[a][b][m][n] = (f32x4){0.f, 0.f, 0.f, 0.f}; } while (0)
; template <class Epi, class Sched>
; __device__ __forceinline__ void gemm_phase(LAS unsigned char* lds, const Gemm g, const Sched& S, const Epi& E, int wid) {
;     ...
;     Unit cur, nxt; int ui = 0;
;     if (!S.next(0, cur)) return;
;     f32x4 acc[2][2][4][2];
;     PG8_ZERO();
;     ...
;         for (int t = 0; t < nt; t += 2) {
;             const bool last = (t == nt - 2);
;             const char* a1 = cA + (size_t)(t + 1) * kstep;
;             const char* a2 = last ? nA : cA + (size_t)(t + 2) * kstep; const char* b2 = last ? nB : cB + (size_t)(t + 2) * kstep;
;             const char* a3 = a2 + kstep; const char* b3 = b2 + kstep;
.LBB0_2322:
	s_add_u32 s31, s4, 0x100
	v_mov_b32_e32 v0, 0
	s_addc_u32 s35, s5, 0
	s_mov_b32 s64, -2
	v_mov_b32_e32 v1, v0
	v_mov_b32_e32 v2, v0
	v_mov_b32_e32 v3, v0
	v_mov_b32_e32 v4, v0
	v_mov_b32_e32 v5, v0
	v_mov_b32_e32 v6, v0
	v_mov_b32_e32 v7, v0
	v_mov_b32_e32 v16, v0
	v_mov_b32_e32 v17, v0
	v_mov_b32_e32 v18, v0
	v_mov_b32_e32 v19, v0
	v_mov_b32_e32 v20, v0
	v_mov_b32_e32 v21, v0
	v_mov_b32_e32 v22, v0
	v_mov_b32_e32 v23, v0
	v_mov_b32_e32 v32, v0
	v_mov_b32_e32 v33, v0
	v_mov_b32_e32 v34, v0
	v_mov_b32_e32 v35, v0
	v_mov_b32_e32 v36, v0
	v_mov_b32_e32 v37, v0
	v_mov_b32_e32 v38, v0
	v_mov_b32_e32 v39, v0
	v_mov_b32_e32 v48, v0
	v_mov_b32_e32 v49, v0
	v_mov_b32_e32 v50, v0
	v_mov_b32_e32 v51, v0
	v_mov_b32_e32 v52, v0
	v_mov_b32_e32 v53, v0
	v_mov_b32_e32 v54, v0
	v_mov_b32_e32 v55, v0
	v_mov_b32_e32 v8, v0
	v_mov_b32_e32 v9, v0
	v_mov_b32_e32 v10, v0
	v_mov_b32_e32 v11, v0
	v_mov_b32_e32 v12, v0
	v_mov_b32_e32 v13, v0
	v_mov_b32_e32 v14, v0
	v_mov_b32_e32 v15, v0
	v_mov_b32_e32 v24, v0
	v_mov_b32_e32 v25, v0
	v_mov_b32_e32 v26, v0
	v_mov_b32_e32 v27, v0
	v_mov_b32_e32 v28, v0
	v_mov_b32_e32 v29, v0
	v_mov_b32_e32 v30, v0
	v_mov_b32_e32 v31, v0
	v_mov_b32_e32 v40, v0
	v_mov_b32_e32 v41, v0
	v_mov_b32_e32 v42, v0
	v_mov_b32_e32 v43, v0
	v_mov_b32_e32 v44, v0
	v_mov_b32_e32 v45, v0
	v_mov_b32_e32 v46, v0
	v_mov_b32_e32 v47, v0
	v_mov_b32_e32 v56, v0
	v_mov_b32_e32 v57, v0
	v_mov_b32_e32 v58, v0
	v_mov_b32_e32 v59, v0
	v_mov_b32_e32 v60, v0
	v_mov_b32_e32 v61, v0
	v_mov_b32_e32 v62, v0
	v_mov_b32_e32 v63, v0
	v_mov_b32_e32 v64, v0
	v_mov_b32_e32 v65, v0
	v_mov_b32_e32 v66, v0
	v_mov_b32_e32 v67, v0
	v_mov_b32_e32 v68, v0
	v_mov_b32_e32 v69, v0
	v_mov_b32_e32 v70, v0
	v_mov_b32_e32 v71, v0
	v_mov_b32_e32 v80, v0
	v_mov_b32_e32 v81, v0
	v_mov_b32_e32 v82, v0
	v_mov_b32_e32 v83, v0
	v_mov_b32_e32 v84, v0
	v_mov_b32_e32 v85, v0
	v_mov_b32_e32 v86, v0
	v_mov_b32_e32 v87, v0
	v_mov_b32_e32 v96, v0
	v_mov_b32_e32 v97, v0
	v_mov_b32_e32 v98, v0
	v_mov_b32_e32 v99, v0
	v_mov_b32_e32 v100, v0
	v_mov_b32_e32 v101, v0
	v_mov_b32_e32 v102, v0
	v_mov_b32_e32 v103, v0
	v_mov_b32_e32 v112, v0
	v_mov_b32_e32 v113, v0
	v_mov_b32_e32 v114, v0
	v_mov_b32_e32 v115, v0
	v_mov_b32_e32 v116, v0
	v_mov_b32_e32 v117, v0
	v_mov_b32_e32 v118, v0
	v_mov_b32_e32 v119, v0
	v_mov_b32_e32 v72, v0
	v_mov_b32_e32 v73, v0
	v_mov_b32_e32 v74, v0
	v_mov_b32_e32 v75, v0
	v_mov_b32_e32 v76, v0
	v_mov_b32_e32 v77, v0
	v_mov_b32_e32 v78, v0
	v_mov_b32_e32 v79, v0
	v_mov_b32_e32 v88, v0
	v_mov_b32_e32 v89, v0
	v_mov_b32_e32 v90, v0
	v_mov_b32_e32 v91, v0
	v_mov_b32_e32 v92, v0
	v_mov_b32_e32 v93, v0
	v_mov_b32_e32 v94, v0
	v_mov_b32_e32 v95, v0
	v_mov_b32_e32 v104, v0
	v_mov_b32_e32 v105, v0
	v_mov_b32_e32 v106, v0
	v_mov_b32_e32 v107, v0
	v_mov_b32_e32 v108, v0
	v_mov_b32_e32 v109, v0
	v_mov_b32_e32 v110, v0
	v_mov_b32_e32 v111, v0
	v_mov_b32_e32 v120, v0
	v_mov_b32_e32 v121, v0
	v_mov_b32_e32 v122, v0
	v_mov_b32_e32 v123, v0
	v_mov_b32_e32 v124, v0
	v_mov_b32_e32 v125, v0
	v_mov_b32_e32 v126, v0
	v_mov_b32_e32 v127, v0
	.p2alignl 6, 3212836864
